# v21 + low-rank pre-pass task loop rewritten: all 32 activation loads of a task issued up front, LDS weight fragments with 3-pair lookahead
# speedup vs baseline: 1.0118x; 1.0030x over previous
.LBB0_176:
	s_add_i32 s16, s16, s17
	ds_read_b128 v[76:79], v75
	ds_read_b128 v[80:83], v75 offset:33024
	ds_read_b128 v[84:87], v75 offset:64
	ds_read_b128 v[88:91], v75 offset:33088
	ds_read_b128 v[92:95], v75 offset:128
	ds_read_b128 v[96:99], v75 offset:33152
	ds_read_b128 v[100:103], v75 offset:192
	ds_read_b128 v[104:107], v75 offset:33216
	s_waitcnt vmcnt(31) lgkmcnt(6)
	v_mfma_f32_16x16x32_bf16 v[224:227], v[76:79], v[0:3], 0
	v_mfma_f32_16x16x32_bf16 v[228:231], v[80:83], v[0:3], 0
	ds_read_b128 v[76:79], v75 offset:256
	ds_read_b128 v[80:83], v75 offset:33280
	s_waitcnt vmcnt(30) lgkmcnt(6)
	v_mfma_f32_16x16x32_bf16 v[224:227], v[84:87], v[8:11], v[224:227]
	v_mfma_f32_16x16x32_bf16 v[228:231], v[88:91], v[8:11], v[228:231]
	ds_read_b128 v[84:87], v75 offset:320
	ds_read_b128 v[88:91], v75 offset:33344
	s_waitcnt vmcnt(29) lgkmcnt(6)
	v_mfma_f32_16x16x32_bf16 v[224:227], v[92:95], v[4:7], v[224:227]
	v_mfma_f32_16x16x32_bf16 v[228:231], v[96:99], v[4:7], v[228:231]
	ds_read_b128 v[92:95], v75 offset:384
	ds_read_b128 v[96:99], v75 offset:33408
	s_waitcnt vmcnt(28) lgkmcnt(6)
	v_mfma_f32_16x16x32_bf16 v[224:227], v[100:103], v[16:19], v[224:227]
	v_mfma_f32_16x16x32_bf16 v[228:231], v[104:107], v[16:19], v[228:231]
	ds_read_b128 v[100:103], v75 offset:448
	ds_read_b128 v[104:107], v75 offset:33472
	s_waitcnt vmcnt(27) lgkmcnt(6)
	v_mfma_f32_16x16x32_bf16 v[224:227], v[76:79], v[12:15], v[224:227]
	v_mfma_f32_16x16x32_bf16 v[228:231], v[80:83], v[12:15], v[228:231]
	ds_read_b128 v[76:79], v75 offset:512
	ds_read_b128 v[80:83], v75 offset:33536
	s_waitcnt vmcnt(26) lgkmcnt(6)
	v_mfma_f32_16x16x32_bf16 v[224:227], v[84:87], v[24:27], v[224:227]
	v_mfma_f32_16x16x32_bf16 v[228:231], v[88:91], v[24:27], v[228:231]
	ds_read_b128 v[84:87], v75 offset:576
	ds_read_b128 v[88:91], v75 offset:33600
	s_waitcnt vmcnt(25) lgkmcnt(6)
	v_mfma_f32_16x16x32_bf16 v[224:227], v[92:95], v[20:23], v[224:227]
	v_mfma_f32_16x16x32_bf16 v[228:231], v[96:99], v[20:23], v[228:231]
	ds_read_b128 v[92:95], v75 offset:640
	ds_read_b128 v[96:99], v75 offset:33664
	s_waitcnt vmcnt(24) lgkmcnt(6)
	v_mfma_f32_16x16x32_bf16 v[224:227], v[100:103], v[32:35], v[224:227]
	v_mfma_f32_16x16x32_bf16 v[228:231], v[104:107], v[32:35], v[228:231]
	ds_read_b128 v[100:103], v75 offset:704
	ds_read_b128 v[104:107], v75 offset:33728
	s_waitcnt vmcnt(23) lgkmcnt(6)
	v_mfma_f32_16x16x32_bf16 v[224:227], v[76:79], v[28:31], v[224:227]
	v_mfma_f32_16x16x32_bf16 v[228:231], v[80:83], v[28:31], v[228:231]
	ds_read_b128 v[76:79], v75 offset:768
	ds_read_b128 v[80:83], v75 offset:33792
	s_waitcnt vmcnt(22) lgkmcnt(6)
	v_mfma_f32_16x16x32_bf16 v[224:227], v[84:87], v[40:43], v[224:227]
	v_mfma_f32_16x16x32_bf16 v[228:231], v[88:91], v[40:43], v[228:231]
	ds_read_b128 v[84:87], v75 offset:832
	ds_read_b128 v[88:91], v75 offset:33856
	s_waitcnt vmcnt(21) lgkmcnt(6)
	v_mfma_f32_16x16x32_bf16 v[224:227], v[92:95], v[36:39], v[224:227]
	v_mfma_f32_16x16x32_bf16 v[228:231], v[96:99], v[36:39], v[228:231]
	ds_read_b128 v[92:95], v75 offset:896
	ds_read_b128 v[96:99], v75 offset:33920
	s_waitcnt vmcnt(20) lgkmcnt(6)
	v_mfma_f32_16x16x32_bf16 v[224:227], v[100:103], v[44:47], v[224:227]
	v_mfma_f32_16x16x32_bf16 v[228:231], v[104:107], v[44:47], v[228:231]
	ds_read_b128 v[100:103], v75 offset:960
	ds_read_b128 v[104:107], v75 offset:33984
	s_waitcnt vmcnt(19) lgkmcnt(6)
	v_mfma_f32_16x16x32_bf16 v[224:227], v[76:79], v[52:55], v[224:227]
	v_mfma_f32_16x16x32_bf16 v[228:231], v[80:83], v[52:55], v[228:231]
	ds_read_b128 v[76:79], v75 offset:1024
	ds_read_b128 v[80:83], v75 offset:34048
	s_waitcnt vmcnt(18) lgkmcnt(6)
	v_mfma_f32_16x16x32_bf16 v[224:227], v[84:87], v[60:63], v[224:227]
	v_mfma_f32_16x16x32_bf16 v[228:231], v[88:91], v[60:63], v[228:231]
	ds_read_b128 v[84:87], v75 offset:1088
	ds_read_b128 v[88:91], v75 offset:34112
	s_waitcnt vmcnt(17) lgkmcnt(6)
	v_mfma_f32_16x16x32_bf16 v[224:227], v[92:95], v[56:59], v[224:227]
	v_mfma_f32_16x16x32_bf16 v[228:231], v[96:99], v[56:59], v[228:231]
	ds_read_b128 v[92:95], v75 offset:1152
	ds_read_b128 v[96:99], v75 offset:34176
	s_waitcnt vmcnt(16) lgkmcnt(6)
	v_mfma_f32_16x16x32_bf16 v[224:227], v[100:103], v[48:51], v[224:227]
	v_mfma_f32_16x16x32_bf16 v[228:231], v[104:107], v[48:51], v[228:231]
	ds_read_b128 v[100:103], v75 offset:1216
	ds_read_b128 v[104:107], v75 offset:34240
	s_waitcnt vmcnt(15) lgkmcnt(6)
	v_mfma_f32_16x16x32_bf16 v[224:227], v[76:79], v[160:163], v[224:227]
	v_mfma_f32_16x16x32_bf16 v[228:231], v[80:83], v[160:163], v[228:231]
	ds_read_b128 v[76:79], v75 offset:1280
	ds_read_b128 v[80:83], v75 offset:34304
	s_waitcnt vmcnt(14) lgkmcnt(6)
	v_mfma_f32_16x16x32_bf16 v[224:227], v[84:87], v[164:167], v[224:227]
	v_mfma_f32_16x16x32_bf16 v[228:231], v[88:91], v[164:167], v[228:231]
	ds_read_b128 v[84:87], v75 offset:1344
	ds_read_b128 v[88:91], v75 offset:34368
	s_waitcnt vmcnt(13) lgkmcnt(6)
	v_mfma_f32_16x16x32_bf16 v[224:227], v[92:95], v[168:171], v[224:227]
	v_mfma_f32_16x16x32_bf16 v[228:231], v[96:99], v[168:171], v[228:231]
	ds_read_b128 v[92:95], v75 offset:1408
	ds_read_b128 v[96:99], v75 offset:34432
	s_waitcnt vmcnt(12) lgkmcnt(6)
	v_mfma_f32_16x16x32_bf16 v[224:227], v[100:103], v[172:175], v[224:227]
	v_mfma_f32_16x16x32_bf16 v[228:231], v[104:107], v[172:175], v[228:231]
	ds_read_b128 v[100:103], v75 offset:1472
	ds_read_b128 v[104:107], v75 offset:34496
	s_waitcnt vmcnt(11) lgkmcnt(6)
	v_mfma_f32_16x16x32_bf16 v[224:227], v[76:79], v[176:179], v[224:227]
	v_mfma_f32_16x16x32_bf16 v[228:231], v[80:83], v[176:179], v[228:231]
	ds_read_b128 v[76:79], v75 offset:1536
	ds_read_b128 v[80:83], v75 offset:34560
	s_waitcnt vmcnt(10) lgkmcnt(6)
	v_mfma_f32_16x16x32_bf16 v[224:227], v[84:87], v[180:183], v[224:227]
	v_mfma_f32_16x16x32_bf16 v[228:231], v[88:91], v[180:183], v[228:231]
	ds_read_b128 v[84:87], v75 offset:1600
	ds_read_b128 v[88:91], v75 offset:34624
	s_waitcnt vmcnt(9) lgkmcnt(6)
	v_mfma_f32_16x16x32_bf16 v[224:227], v[92:95], v[184:187], v[224:227]
	v_mfma_f32_16x16x32_bf16 v[228:231], v[96:99], v[184:187], v[228:231]
	ds_read_b128 v[92:95], v75 offset:1664
	ds_read_b128 v[96:99], v75 offset:34688
	s_waitcnt vmcnt(8) lgkmcnt(6)
	v_mfma_f32_16x16x32_bf16 v[224:227], v[100:103], v[188:191], v[224:227]
	v_mfma_f32_16x16x32_bf16 v[228:231], v[104:107], v[188:191], v[228:231]
	ds_read_b128 v[100:103], v75 offset:1728
	ds_read_b128 v[104:107], v75 offset:34752
	s_waitcnt vmcnt(7) lgkmcnt(6)
	v_mfma_f32_16x16x32_bf16 v[224:227], v[76:79], v[192:195], v[224:227]
	v_mfma_f32_16x16x32_bf16 v[228:231], v[80:83], v[192:195], v[228:231]
	ds_read_b128 v[76:79], v75 offset:1792
	ds_read_b128 v[80:83], v75 offset:34816
	s_waitcnt vmcnt(6) lgkmcnt(6)
	v_mfma_f32_16x16x32_bf16 v[224:227], v[84:87], v[196:199], v[224:227]
	v_mfma_f32_16x16x32_bf16 v[228:231], v[88:91], v[196:199], v[228:231]
	ds_read_b128 v[84:87], v75 offset:1856
	ds_read_b128 v[88:91], v75 offset:34880
	s_waitcnt vmcnt(5) lgkmcnt(6)
	v_mfma_f32_16x16x32_bf16 v[224:227], v[92:95], v[200:203], v[224:227]
	v_mfma_f32_16x16x32_bf16 v[228:231], v[96:99], v[200:203], v[228:231]
	ds_read_b128 v[92:95], v75 offset:1920
	ds_read_b128 v[96:99], v75 offset:34944
	s_waitcnt vmcnt(4) lgkmcnt(6)
	v_mfma_f32_16x16x32_bf16 v[224:227], v[100:103], v[204:207], v[224:227]
	v_mfma_f32_16x16x32_bf16 v[228:231], v[104:107], v[204:207], v[228:231]
	ds_read_b128 v[100:103], v75 offset:1984
	ds_read_b128 v[104:107], v75 offset:35008
	s_waitcnt vmcnt(3) lgkmcnt(6)
	v_mfma_f32_16x16x32_bf16 v[224:227], v[76:79], v[208:211], v[224:227]
	v_mfma_f32_16x16x32_bf16 v[228:231], v[80:83], v[208:211], v[228:231]
	s_waitcnt vmcnt(2) lgkmcnt(4)
	v_mfma_f32_16x16x32_bf16 v[224:227], v[84:87], v[212:215], v[224:227]
	v_mfma_f32_16x16x32_bf16 v[228:231], v[88:91], v[212:215], v[228:231]
	s_waitcnt vmcnt(1) lgkmcnt(2)
	v_mfma_f32_16x16x32_bf16 v[224:227], v[92:95], v[216:219], v[224:227]
	v_mfma_f32_16x16x32_bf16 v[228:231], v[96:99], v[216:219], v[228:231]
	s_waitcnt vmcnt(0) lgkmcnt(0)
	v_mfma_f32_16x16x32_bf16 v[224:227], v[100:103], v[220:223], v[224:227]
	v_mfma_f32_16x16x32_bf16 v[228:231], v[104:107], v[220:223], v[228:231]
	v_lshlrev_b64 v[70:71], 7, v[68:69]
	v_add_u32_e32 v69, s16, v73
	v_cmp_lt_i32_e32 vcc, s19, v69
	v_lshl_add_u64 v[70:71], v[66:67], 0, v[70:71]
	v_add_u32_e32 v68, s18, v68
	s_nop 1
	s_or_b64 s[14:15], vcc, s[14:15]
	s_nop 0
	global_store_dwordx4 v[70:71], v[224:227], off
	global_store_dwordx4 v[70:71], v[228:231], off offset:64
	s_andn2_b64 exec, exec, s[14:15]
	s_cbranch_execz .LBB0_179

.Llr_second16:
	global_load_dwordx4 v[160:163], v[70:71], off offset:1024
	global_load_dwordx4 v[164:167], v[70:71], off offset:1088
	global_load_dwordx4 v[168:171], v[70:71], off offset:1152
	global_load_dwordx4 v[172:175], v[70:71], off offset:1216
	global_load_dwordx4 v[176:179], v[70:71], off offset:1280
	global_load_dwordx4 v[180:183], v[70:71], off offset:1344
	global_load_dwordx4 v[184:187], v[70:71], off offset:1408
	global_load_dwordx4 v[188:191], v[70:71], off offset:1472
	global_load_dwordx4 v[192:195], v[70:71], off offset:1536
	global_load_dwordx4 v[196:199], v[70:71], off offset:1600
	global_load_dwordx4 v[200:203], v[70:71], off offset:1664
	global_load_dwordx4 v[204:207], v[70:71], off offset:1728
	global_load_dwordx4 v[208:211], v[70:71], off offset:1792
	global_load_dwordx4 v[212:215], v[70:71], off offset:1856
	global_load_dwordx4 v[216:219], v[70:71], off offset:1920
	global_load_dwordx4 v[220:223], v[70:71], off offset:1984
	s_branch .LBB0_176
